# prologue S5 C-table loop: 8 loads in flight then 8 stores instead of 8 serial trips (P1..P2 code shifted by -4 bytes)
# baseline (speedup 1.0000x reference)
.LBB0_124:
	v_writelane_b32 v253, s48, 51
	s_nop 1
	v_writelane_b32 v253, s49, 52
	v_writelane_b32 v253, s50, 53
	v_writelane_b32 v253, s51, 54
	v_writelane_b32 v253, s52, 55
	v_writelane_b32 v253, s53, 56
	v_writelane_b32 v253, s54, 57
	v_writelane_b32 v253, s55, 58
	v_writelane_b32 v253, s56, 59
	v_writelane_b32 v253, s57, 60
	v_writelane_b32 v253, s58, 61
	v_writelane_b32 v253, s59, 62
	v_writelane_b32 v253, s60, 63
	v_writelane_b32 v254, s61, 0
	v_writelane_b32 v254, s62, 1
	v_readlane_b32 s0, v253, 49
	v_writelane_b32 v254, s63, 2
	v_readlane_b32 s1, v253, 50
	s_or_b64 exec, exec, s[0:1]
	s_mov_b32 s0, 0x100000
	v_cmp_gt_i32_e32 vcc, s0, v10
	s_mov_b64 s[2:3], exec
	v_readlane_b32 s52, v253, 8
	v_readlane_b32 s60, v253, 16
	v_readlane_b32 s61, v253, 17
	v_readlane_b32 s62, v253, 18
	v_readlane_b32 s63, v253, 19
	v_readlane_b32 s64, v253, 20
	v_readlane_b32 s65, v253, 21
	v_readlane_b32 s66, v253, 22
	v_readlane_b32 s67, v253, 23
	v_readlane_b32 s12, v253, 51
	v_readlane_b32 s60, v253, 24
	s_and_b64 s[0:1], s[2:3], vcc
	v_readlane_b32 s53, v253, 9
	v_readlane_b32 s56, v253, 12
	v_readlane_b32 s57, v253, 13
	v_readlane_b32 s20, v253, 59
	v_readlane_b32 s21, v253, 60
	v_readlane_b32 s22, v253, 61
	v_readlane_b32 s23, v253, 62
	v_readlane_b32 s64, v253, 28
	v_readlane_b32 s65, v253, 29
	v_readlane_b32 s68, v253, 32
	v_readlane_b32 s69, v253, 33
	v_readlane_b32 s54, v253, 10
	v_readlane_b32 s55, v253, 11
	v_readlane_b32 s58, v253, 14
	v_readlane_b32 s59, v253, 15
	v_readlane_b32 s13, v253, 52
	v_readlane_b32 s14, v253, 53
	v_readlane_b32 s15, v253, 54
	v_readlane_b32 s16, v253, 55
	v_readlane_b32 s17, v253, 56
	v_readlane_b32 s18, v253, 57
	v_readlane_b32 s19, v253, 58
	v_readlane_b32 s24, v253, 63
	v_readlane_b32 s25, v254, 0
	v_readlane_b32 s26, v254, 1
	v_readlane_b32 s27, v254, 2
	v_readlane_b32 s61, v253, 25
	v_readlane_b32 s62, v253, 26
	v_readlane_b32 s63, v253, 27
	v_readlane_b32 s66, v253, 30
	v_readlane_b32 s67, v253, 31
	v_readlane_b32 s70, v253, 34
	v_readlane_b32 s71, v253, 35
	v_readlane_b32 s72, v253, 36
	v_readlane_b32 s73, v253, 37
	v_readlane_b32 s74, v253, 38
	v_readlane_b32 s75, v253, 39
	s_mov_b64 exec, s[0:1]
	s_cbranch_execz .LBB0_133
	v_and_b32_e32 v1, 1, v8
	v_cmp_eq_u32_e32 vcc, 1, v1
	v_lshlrev_b32_e32 v24, 31, v1
	v_lshl_add_u64 v[22:23], v[10:11], 1, s[94:95]
	s_mov_b64 s[0:1], 0x200000
	v_lshl_add_u64 v[22:23], v[22:23], 0, s[0:1]
	v_bfe_u32 v7, v10, 7, 5
	v_cmp_gt_u32_e64 s[12:13], 16, v7
	v_ashrrev_i32_e32 v4, 12, v10
	v_lshlrev_b32_e32 v4, 10, v4
	v_lshlrev_b32_e32 v6, 6, v7
	v_bfe_u32 v5, v10, 1, 6
	v_or3_b32 v4, v4, v6, v5
	v_mov_b32_e32 v5, 0
	v_mov_b32_e32 v2, s20
	v_mov_b32_e32 v3, s21
	v_mov_b32_e32 v6, s22
	v_mov_b32_e32 v7, s23
	v_cndmask_b32_e32 v2, v2, v6, vcc
	v_cndmask_b32_e32 v3, v3, v7, vcc
	v_lshl_add_u64 v[20:21], v[4:5], 2, v[2:3]
	s_mov_b64 s[0:1], 0x20000
	v_mov_b32_e32 v12, 0
	v_mov_b32_e32 v13, 0
	v_mov_b32_e32 v14, 0
	v_mov_b32_e32 v15, 0
	v_mov_b32_e32 v16, 0
	v_mov_b32_e32 v17, 0
	v_mov_b32_e32 v18, 0
	v_mov_b32_e32 v19, 0
	s_and_b64 exec, exec, s[12:13]
	global_load_dword v12, v[20:21], off
	v_lshl_add_u64 v[20:21], v[20:21], 0, s[0:1]
	global_load_dword v13, v[20:21], off
	v_lshl_add_u64 v[20:21], v[20:21], 0, s[0:1]
	global_load_dword v14, v[20:21], off
	v_lshl_add_u64 v[20:21], v[20:21], 0, s[0:1]
	global_load_dword v15, v[20:21], off
	v_lshl_add_u64 v[20:21], v[20:21], 0, s[0:1]
	global_load_dword v16, v[20:21], off
	v_lshl_add_u64 v[20:21], v[20:21], 0, s[0:1]
	global_load_dword v17, v[20:21], off
	v_lshl_add_u64 v[20:21], v[20:21], 0, s[0:1]
	global_load_dword v18, v[20:21], off
	v_lshl_add_u64 v[20:21], v[20:21], 0, s[0:1]
	global_load_dword v19, v[20:21], off
	s_mov_b64 exec, s[2:3]
	s_movk_i32 s14, 0x7fff
	s_mov_b64 s[0:1], 0x40000
	s_waitcnt vmcnt(0)
	v_xor_b32_e32 v12, v12, v24
	v_bfe_u32 v4, v12, 16, 1
	v_add3_u32 v4, v12, v4, s14
	global_store_short_d16_hi v[22:23], v4, off
	v_lshl_add_u64 v[22:23], v[22:23], 0, s[0:1]
	v_xor_b32_e32 v13, v13, v24
	v_bfe_u32 v4, v13, 16, 1
	v_add3_u32 v4, v13, v4, s14
	global_store_short_d16_hi v[22:23], v4, off
	v_lshl_add_u64 v[22:23], v[22:23], 0, s[0:1]
	v_xor_b32_e32 v14, v14, v24
	v_bfe_u32 v4, v14, 16, 1
	v_add3_u32 v4, v14, v4, s14
	global_store_short_d16_hi v[22:23], v4, off
	v_lshl_add_u64 v[22:23], v[22:23], 0, s[0:1]
	v_xor_b32_e32 v15, v15, v24
	v_bfe_u32 v4, v15, 16, 1
	v_add3_u32 v4, v15, v4, s14
	global_store_short_d16_hi v[22:23], v4, off
	v_lshl_add_u64 v[22:23], v[22:23], 0, s[0:1]
	v_xor_b32_e32 v16, v16, v24
	v_bfe_u32 v4, v16, 16, 1
	v_add3_u32 v4, v16, v4, s14
	global_store_short_d16_hi v[22:23], v4, off
	v_lshl_add_u64 v[22:23], v[22:23], 0, s[0:1]
	v_xor_b32_e32 v17, v17, v24
	v_bfe_u32 v4, v17, 16, 1
	v_add3_u32 v4, v17, v4, s14
	global_store_short_d16_hi v[22:23], v4, off
	v_lshl_add_u64 v[22:23], v[22:23], 0, s[0:1]
	v_xor_b32_e32 v18, v18, v24
	v_bfe_u32 v4, v18, 16, 1
	v_add3_u32 v4, v18, v4, s14
	global_store_short_d16_hi v[22:23], v4, off
	v_lshl_add_u64 v[22:23], v[22:23], 0, s[0:1]
	v_xor_b32_e32 v19, v19, v24
	v_bfe_u32 v4, v19, 16, 1
	v_add3_u32 v4, v19, v4, s14
	global_store_short_d16_hi v[22:23], v4, off
